# moba_pre V^T staging: 8 loads issued back to back then 8 LDS writes with counted waits (4 dependent round trips -> 1)
# speedup vs baseline: 1.0202x; 1.0010x over previous
.LBB0_168:
	v_add_u32_e32 v13, s0, v0
	v_ashrrev_i32_e32 v22, 4, v13
	v_mov_b64_e32 v[14:15], s[88:89]
	v_add_u32_e32 v13, 0x200, v13
	v_add_u32_e32 v16, s13, v22
	s_lshl_b32 s20, s16, 1
	v_ashrrev_i32_e32 v13, 4, v13
	v_mad_i64_i32 v[16:17], s[14:15], v16, s72, v[14:15]
	v_add_u32_e32 v18, s13, v13
	v_lshl_add_u64 v[16:17], v[16:17], 0, s[20:21]
	v_mad_i64_i32 v[14:15], s[14:15], v18, s72, v[14:15]
	v_lshl_add_u64 v[16:17], v[16:17], 0, v[2:3]
	v_lshl_add_u64 v[14:15], v[14:15], 0, s[20:21]
	v_add_co_u32_e32 v16, vcc, 0x1000, v16
	v_lshl_add_u64 v[14:15], v[14:15], 0, v[2:3]
	s_nop 0
	v_addc_co_u32_e32 v17, vcc, 0, v17, vcc
	v_add_co_u32_e32 v18, vcc, 0x1000, v14
	s_addk_i32 s0, 0x400
	s_nop 0
	v_addc_co_u32_e32 v19, vcc, 0, v15, vcc
	global_load_dwordx4 v[108:111], v[16:17], off offset:2048
	global_load_dwordx4 v[112:115], v[18:19], off offset:2048
	v_mad_u64_u32 v[144:145], s[14:15], v22, s64, v[6:7]
	v_mad_u64_u32 v[146:147], s[14:15], v13, s64, v[6:7]
	v_add_u32_e32 v13, s0, v0
	v_ashrrev_i32_e32 v22, 4, v13
	v_mov_b64_e32 v[14:15], s[88:89]
	v_add_u32_e32 v13, 0x200, v13
	v_add_u32_e32 v16, s13, v22
	s_lshl_b32 s20, s16, 1
	v_ashrrev_i32_e32 v13, 4, v13
	v_mad_i64_i32 v[16:17], s[14:15], v16, s72, v[14:15]
	v_add_u32_e32 v18, s13, v13
	v_lshl_add_u64 v[16:17], v[16:17], 0, s[20:21]
	v_mad_i64_i32 v[14:15], s[14:15], v18, s72, v[14:15]
	v_lshl_add_u64 v[16:17], v[16:17], 0, v[2:3]
	v_lshl_add_u64 v[14:15], v[14:15], 0, s[20:21]
	v_add_co_u32_e32 v16, vcc, 0x1000, v16
	v_lshl_add_u64 v[14:15], v[14:15], 0, v[2:3]
	s_nop 0
	v_addc_co_u32_e32 v17, vcc, 0, v17, vcc
	v_add_co_u32_e32 v18, vcc, 0x1000, v14
	s_addk_i32 s0, 0x400
	s_nop 0
	v_addc_co_u32_e32 v19, vcc, 0, v15, vcc
	global_load_dwordx4 v[116:119], v[16:17], off offset:2048
	global_load_dwordx4 v[120:123], v[18:19], off offset:2048
	v_mad_u64_u32 v[148:149], s[14:15], v22, s64, v[6:7]
	v_mad_u64_u32 v[150:151], s[14:15], v13, s64, v[6:7]
	v_add_u32_e32 v13, s0, v0
	v_ashrrev_i32_e32 v22, 4, v13
	v_mov_b64_e32 v[14:15], s[88:89]
	v_add_u32_e32 v13, 0x200, v13
	v_add_u32_e32 v16, s13, v22
	s_lshl_b32 s20, s16, 1
	v_ashrrev_i32_e32 v13, 4, v13
	v_mad_i64_i32 v[16:17], s[14:15], v16, s72, v[14:15]
	v_add_u32_e32 v18, s13, v13
	v_lshl_add_u64 v[16:17], v[16:17], 0, s[20:21]
	v_mad_i64_i32 v[14:15], s[14:15], v18, s72, v[14:15]
	v_lshl_add_u64 v[16:17], v[16:17], 0, v[2:3]
	v_lshl_add_u64 v[14:15], v[14:15], 0, s[20:21]
	v_add_co_u32_e32 v16, vcc, 0x1000, v16
	v_lshl_add_u64 v[14:15], v[14:15], 0, v[2:3]
	s_nop 0
	v_addc_co_u32_e32 v17, vcc, 0, v17, vcc
	v_add_co_u32_e32 v18, vcc, 0x1000, v14
	s_addk_i32 s0, 0x400
	s_nop 0
	v_addc_co_u32_e32 v19, vcc, 0, v15, vcc
	global_load_dwordx4 v[124:127], v[16:17], off offset:2048
	global_load_dwordx4 v[128:131], v[18:19], off offset:2048
	v_mad_u64_u32 v[152:153], s[14:15], v22, s64, v[6:7]
	v_mad_u64_u32 v[154:155], s[14:15], v13, s64, v[6:7]
	v_add_u32_e32 v13, s0, v0
	v_ashrrev_i32_e32 v22, 4, v13
	v_mov_b64_e32 v[14:15], s[88:89]
	v_add_u32_e32 v13, 0x200, v13
	v_add_u32_e32 v16, s13, v22
	s_lshl_b32 s20, s16, 1
	v_ashrrev_i32_e32 v13, 4, v13
	v_mad_i64_i32 v[16:17], s[14:15], v16, s72, v[14:15]
	v_add_u32_e32 v18, s13, v13
	v_lshl_add_u64 v[16:17], v[16:17], 0, s[20:21]
	v_mad_i64_i32 v[14:15], s[14:15], v18, s72, v[14:15]
	v_lshl_add_u64 v[16:17], v[16:17], 0, v[2:3]
	v_lshl_add_u64 v[14:15], v[14:15], 0, s[20:21]
	v_add_co_u32_e32 v16, vcc, 0x1000, v16
	v_lshl_add_u64 v[14:15], v[14:15], 0, v[2:3]
	s_nop 0
	v_addc_co_u32_e32 v17, vcc, 0, v17, vcc
	v_add_co_u32_e32 v18, vcc, 0x1000, v14
	s_addk_i32 s0, 0x400
	s_nop 0
	v_addc_co_u32_e32 v19, vcc, 0, v15, vcc
	global_load_dwordx4 v[132:135], v[16:17], off offset:2048
	global_load_dwordx4 v[136:139], v[18:19], off offset:2048
	v_mad_u64_u32 v[156:157], s[14:15], v22, s64, v[6:7]
	v_mad_u64_u32 v[158:159], s[14:15], v13, s64, v[6:7]
	s_waitcnt vmcnt(7)
	ds_write_b128 v144, v[108:111] offset:4096
	s_waitcnt vmcnt(6)
	ds_write_b128 v146, v[112:115] offset:4096
	s_waitcnt vmcnt(5)
	ds_write_b128 v148, v[116:119] offset:4096
	s_waitcnt vmcnt(4)
	ds_write_b128 v150, v[120:123] offset:4096
	s_waitcnt vmcnt(3)
	ds_write_b128 v152, v[124:127] offset:4096
	s_waitcnt vmcnt(2)
	ds_write_b128 v154, v[128:131] offset:4096
	s_waitcnt vmcnt(1)
	ds_write_b128 v156, v[132:135] offset:4096
	s_waitcnt vmcnt(0)
	ds_write_b128 v158, v[136:139] offset:4096
	s_lshl_b32 s0, s12, 9
	s_or_b32 s0, s0, s16
	v_or_b32_e32 v14, s0, v7
	v_ashrrev_i32_e32 v15, 31, v14
	v_readlane_b32 s0, v254, 48
	v_lshlrev_b64 v[14:15], 14, v[14:15]
	v_readlane_b32 s1, v254, 49
	s_lshl_b32 s20, s11, 1
	s_waitcnt lgkmcnt(0)
	v_lshl_add_u64 v[14:15], s[0:1], 0, v[14:15]
	v_lshl_add_u64 v[14:15], v[14:15], 0, s[20:21]
	s_mov_b32 s0, 0
	s_barrier
